# FFN2 final row pass of the first row half moved out of the gate-up tail chunk queue into the static final-phase row loop (same math, different schedule)
# speedup vs baseline: 1.0049x; 1.0049x over previous
;     for (int n = 0; n < max_chunks; ++n) {
;         if (tid == 0) MISC[0] = (int)atomicAdd(ctr, 1u);
;         __syncthreads();
;         const int c = __builtin_amdgcn_readfirstlane(MISC[0]);
;         __syncthreads();
;         if (c >= RP_CHUNKS) break;
;         const int r0 = (chunk0 + c) * 64 + wave * 8;
.LBB0_1719:
	s_or_b64 exec, exec, s[48:49]
	v_mov_b32_e32 v110, s68
	s_waitcnt vmcnt(0) lgkmcnt(0)
	s_barrier
	ds_read_b32 v110, v110
	s_mov_b64 s[48:49], -1
	s_waitcnt lgkmcnt(0)
	s_barrier
	v_readfirstlane_b32 s50, v110
	s_cmpk_gt_i32 s50, -1
	s_cbranch_scc1 .LBB0_1716
	s_lshl_b32 s48, s50, 6
	s_add_i32 s48, s54, s48
	s_ashr_i32 s49, s48, 31
	s_lshl_b64 s[50:51], s[48:49], 12
	v_lshl_add_u64 v[110:111], v[74:75], 0, s[50:51]
	s_lshl_b64 s[50:51], s[48:49], 13
	v_lshl_add_u64 v[112:113], v[76:77], 0, s[50:51]
	s_mov_b32 s49, -2
	s_branch .LBB0_1722

;     for (int n = 0; n < max_chunks; ++n) {
;         if (tid == 0) MISC[0] = (int)atomicAdd(ctr, 1u);
;         __syncthreads();
;         const int c = __builtin_amdgcn_readfirstlane(MISC[0]);
;         __syncthreads();
;         if (c >= RP_CHUNKS) break;
;         const int r0 = (chunk0 + c) * 64 + wave * 8;
.LBB0_1817:
	s_or_b64 exec, exec, s[26:27]
	v_mov_b32_e32 v110, s68
	s_waitcnt lgkmcnt(0)
	s_barrier
	ds_read_b32 v110, v110
	s_mov_b64 s[26:27], -1
	s_waitcnt lgkmcnt(0)
	s_barrier
	v_readfirstlane_b32 s28, v110
	s_cmpk_gt_i32 s28, -1
	s_cbranch_scc1 .LBB0_1814
	s_lshl_b32 s26, s28, 6
	s_add_i32 s26, s41, s26
	s_ashr_i32 s27, s26, 31
	s_lshl_b64 s[28:29], s[26:27], 12
	v_lshl_add_u64 v[110:111], v[74:75], 0, s[28:29]
	s_lshl_b64 s[28:29], s[26:27], 13
	v_lshl_add_u64 v[112:113], v[76:77], 0, s[28:29]
	s_mov_b32 s27, -2
	s_branch .LBB0_1820

;     for (int n = 0; n < max_chunks; ++n) {
;         if (tid == 0) MISC[0] = (int)atomicAdd(ctr, 1u);
;         __syncthreads();
;         const int c = __builtin_amdgcn_readfirstlane(MISC[0]);
;         __syncthreads();
;         if (c >= RP_CHUNKS) break;
;         const int r0 = (chunk0 + c) * 64 + wave * 8;
.LBB0_1886:
	s_or_b64 exec, exec, s[4:5]
	v_mov_b32_e32 v120, s12
	s_waitcnt lgkmcnt(0)
	s_barrier
	ds_read_b32 v120, v120
	s_mov_b64 s[4:5], -1
	s_waitcnt lgkmcnt(0)
	s_barrier
	v_readfirstlane_b32 s6, v120
	s_cmpk_gt_i32 s6, -1
	s_cbranch_scc1 .LBB0_1883
	s_lshl_b32 s4, s6, 6
	s_add_i32 s4, s11, s4
	s_ashr_i32 s5, s4, 31
	s_lshl_b64 s[6:7], s[4:5], 12
	v_lshl_add_u64 v[120:121], v[84:85], 0, s[6:7]
	s_lshl_b64 s[6:7], s[4:5], 13
	v_lshl_add_u64 v[122:123], v[86:87], 0, s[6:7]
	s_mov_b32 s5, -2
	s_branch .LBB0_1889

; template <int MODE>
; __device__ __forceinline__ void row_pass(const Params& p, int wave, int lane, const float* gpost, const float* gnext, const bf16_t* Dsrc, bf16_t* U, float coef, int rbeg) {
;     const int gw = blockIdx.x * 8 + wave, NGW = gridDim.x * 8;
;     for (int r = rbeg + gw; r < ROWSP; r += 2 * NGW) {
;         f32x4 ha[8], hb[8]; u32x2 da[8], db[8];
;         row_load<MODE>(p, r, lane, Dsrc, ha, da);
;         row_load<MODE>(p, r + NGW, lane, Dsrc, hb, db);
;         row_finish<MODE>(p, r, lane, gpost, gnext, U, coef, ha, da);
;         row_finish<MODE>(p, r + NGW, lane, gpost, gnext, U, coef, hb, db);
;     }
; }
; __global__ void __launch_bounds__(512, 2) fwd_kernel(Params p) {
;     ...
;                 row_pass<3>(p, wave, lane, p.in[24], nullptr, Breg, nullptr, 0.5f, 16384);
.LBB0_1897:
	s_lshl_b32 s0, s2, 3
	s_add_i32 s0, s0, s10
	s_add_i32 s2, s0, 0
	s_cmp_gt_i32 s2, 0x80ff
	s_cbranch_scc1 .LBB0_1908
	s_waitcnt vmcnt(0)
	v_lshlrev_b32_e32 v0, 3, v64
	v_mov_b32_e32 v1, 0
	v_lshl_add_u64 v[2:3], s[16:17], 0, v[0:1]
	s_mov_b64 s[0:1], 0xa2f1d00
	s_lshl_b32 s8, s22, 3
	v_lshl_add_u64 v[84:85], v[2:3], 0, s[0:1]
	v_mov_b32_e32 v120, 0x358637bd
	s_mov_b32 s9, 0x800000
	v_mov_b32_e32 v0, v1
	v_mov_b32_e32 v2, v1
	v_mov_b32_e32 v3, v1
	v_mov_b32_e32 v32, v1
	v_mov_b32_e32 v33, v1
	v_mov_b32_e32 v34, v1
	v_mov_b32_e32 v35, v1
	v_mov_b32_e32 v40, v1
	v_mov_b32_e32 v41, v1
	v_mov_b32_e32 v42, v1
	v_mov_b32_e32 v43, v1
	v_mov_b32_e32 v44, v1
	v_mov_b32_e32 v45, v1
	v_mov_b32_e32 v46, v1
	v_mov_b32_e32 v47, v1
	v_mov_b32_e32 v48, v1
	v_mov_b32_e32 v49, v1
	v_mov_b32_e32 v50, v1
	v_mov_b32_e32 v51, v1
	v_mov_b32_e32 v52, v1
	v_mov_b32_e32 v53, v1
	v_mov_b32_e32 v54, v1
	v_mov_b32_e32 v55, v1
	v_mov_b32_e32 v56, v1
	v_mov_b32_e32 v57, v1
	v_mov_b32_e32 v58, v1
	v_mov_b32_e32 v59, v1
	v_mov_b32_e32 v60, v1
	v_mov_b32_e32 v61, v1
	v_mov_b32_e32 v62, v1
	v_mov_b32_e32 v63, v1
	s_branch .LBB0_1900
